# plus MLA in-projection epilogue row sum-of-squares via DPP and permlane16 swap instead of 80 LDS bpermute round trips per tile
# speedup vs baseline: 1.0015x; 1.0015x over previous
; DI bf16 f2bf(float a) { return (bf16)(pack2(a, 0.f) & 0xffffu); }
; DI int crow(int i, int g) { return (i & 3) + 8 * (i >> 2) + 4 * g; }
;     ...
;       bf16* hb = (bf16*)(ws + OFF_HB);
;       if (nt < 5) {
; #pragma unroll
;         for (int j = 0; j < 4; ++j)
; #pragma unroll
;           for (int i = 0; i < 16; ++i) hb[(size_t)(m0 + 32 * w + crow(i, g)) * 640 + n0 + 32 * j + r] = f2bf(acc[j][i]);
.LBB0_236:
	s_ashr_i32 s17, s16, 31
	s_waitcnt vmcnt(6)
	v_add_u32_e32 v94, s4, v144
	v_lshl_add_u64 v[96:97], s[16:17], 1, v[132:133]
	v_cvt_pk_bf16_f32 v64, v48, s0
	v_mad_i64_i32 v[98:99], s[0:1], v94, s55, v[96:97]
	v_or_b32_e32 v92, 1, v94
	global_store_short v[98:99], v64, off
	v_cvt_pk_bf16_f32 v64, v49, s0
	v_mad_i64_i32 v[100:101], s[0:1], v92, s55, v[96:97]
	v_or_b32_e32 v90, 2, v94
	global_store_short v[100:101], v64, off
	v_cvt_pk_bf16_f32 v64, v50, s0
	v_mad_i64_i32 v[102:103], s[0:1], v90, s55, v[96:97]
	v_or_b32_e32 v88, 3, v94
	global_store_short v[102:103], v64, off
	v_cvt_pk_bf16_f32 v64, v51, s0
	s_waitcnt vmcnt(8)
	v_mad_i64_i32 v[104:105], s[0:1], v88, s55, v[96:97]
	v_or_b32_e32 v86, 8, v94
	global_store_short v[104:105], v64, off
	v_cvt_pk_bf16_f32 v64, v52, s0
	v_mad_i64_i32 v[106:107], s[0:1], v86, s55, v[96:97]
	v_or_b32_e32 v84, 9, v94
	global_store_short v[106:107], v64, off
	v_cvt_pk_bf16_f32 v64, v53, s0
	s_waitcnt vmcnt(9)
	v_mad_i64_i32 v[108:109], s[0:1], v84, s55, v[96:97]
	v_or_b32_e32 v82, 10, v94
	global_store_short v[108:109], v64, off
	v_cvt_pk_bf16_f32 v64, v54, s0
	v_mad_i64_i32 v[110:111], s[0:1], v82, s55, v[96:97]
	v_or_b32_e32 v80, 11, v94
	global_store_short v[110:111], v64, off
	v_cvt_pk_bf16_f32 v64, v55, s0
	s_waitcnt vmcnt(10)
	v_mad_i64_i32 v[112:113], s[0:1], v80, s55, v[96:97]
	v_or_b32_e32 v78, 16, v94
	global_store_short v[112:113], v64, off
	v_cvt_pk_bf16_f32 v64, v56, s0
	v_mad_i64_i32 v[114:115], s[0:1], v78, s55, v[96:97]
	v_or_b32_e32 v76, 17, v94
	global_store_short v[114:115], v64, off
	v_cvt_pk_bf16_f32 v64, v57, s0
	s_waitcnt vmcnt(11)
	v_mad_i64_i32 v[116:117], s[0:1], v76, s55, v[96:97]
	v_or_b32_e32 v74, 18, v94
	global_store_short v[116:117], v64, off
	v_cvt_pk_bf16_f32 v64, v58, s0
	v_mad_i64_i32 v[118:119], s[0:1], v74, s55, v[96:97]
	v_or_b32_e32 v72, 19, v94
	global_store_short v[118:119], v64, off
	v_cvt_pk_bf16_f32 v64, v59, s0
	s_waitcnt vmcnt(12)
	v_mad_i64_i32 v[120:121], s[0:1], v72, s55, v[96:97]
	v_or_b32_e32 v70, 24, v94
	global_store_short v[120:121], v64, off
	v_cvt_pk_bf16_f32 v64, v60, s0
	v_mad_i64_i32 v[122:123], s[0:1], v70, s55, v[96:97]
	v_or_b32_e32 v68, 25, v94
	global_store_short v[122:123], v64, off
	v_cvt_pk_bf16_f32 v64, v61, s0
	s_waitcnt vmcnt(13)
	v_mad_i64_i32 v[124:125], s[0:1], v68, s55, v[96:97]
	v_or_b32_e32 v66, 26, v94
	global_store_short v[124:125], v64, off
	v_cvt_pk_bf16_f32 v64, v62, s0
	v_mad_i64_i32 v[126:127], s[0:1], v66, s55, v[96:97]
	global_store_short v[126:127], v64, off
	v_or_b32_e32 v64, 27, v94
	v_cvt_pk_bf16_f32 v65, v63, s0
	v_mad_i64_i32 v[96:97], s[0:1], v64, s55, v[96:97]
	global_store_short v[96:97], v65, off
	s_nop 0
	v_cvt_pk_bf16_f32 v65, v32, s0
	global_store_short v[98:99], v65, off offset:64
	v_cvt_pk_bf16_f32 v65, v33, s0
	global_store_short v[100:101], v65, off offset:64
	v_cvt_pk_bf16_f32 v65, v34, s0
	global_store_short v[102:103], v65, off offset:64
	v_cvt_pk_bf16_f32 v65, v35, s0
	global_store_short v[104:105], v65, off offset:64
	v_cvt_pk_bf16_f32 v65, v36, s0
	global_store_short v[106:107], v65, off offset:64
	v_cvt_pk_bf16_f32 v65, v37, s0
	global_store_short v[108:109], v65, off offset:64
	v_cvt_pk_bf16_f32 v65, v38, s0
	global_store_short v[110:111], v65, off offset:64
	v_cvt_pk_bf16_f32 v65, v39, s0
	global_store_short v[112:113], v65, off offset:64
	v_cvt_pk_bf16_f32 v65, v40, s0
	global_store_short v[114:115], v65, off offset:64
	v_cvt_pk_bf16_f32 v65, v41, s0
	global_store_short v[116:117], v65, off offset:64
	v_cvt_pk_bf16_f32 v65, v42, s0
	global_store_short v[118:119], v65, off offset:64
	v_cvt_pk_bf16_f32 v65, v43, s0
	global_store_short v[120:121], v65, off offset:64
	v_cvt_pk_bf16_f32 v65, v44, s0
	global_store_short v[122:123], v65, off offset:64
	v_cvt_pk_bf16_f32 v65, v45, s0
	global_store_short v[124:125], v65, off offset:64
	v_cvt_pk_bf16_f32 v65, v46, s0
	global_store_short v[126:127], v65, off offset:64
	v_cvt_pk_bf16_f32 v65, v47, s0
	global_store_short v[96:97], v65, off offset:64
	v_cvt_pk_bf16_f32 v65, v16, s0
	global_store_short v[98:99], v65, off offset:128
	v_cvt_pk_bf16_f32 v65, v17, s0
	global_store_short v[100:101], v65, off offset:128
	v_cvt_pk_bf16_f32 v65, v18, s0
	global_store_short v[102:103], v65, off offset:128
	v_cvt_pk_bf16_f32 v65, v19, s0
	global_store_short v[104:105], v65, off offset:128
	v_cvt_pk_bf16_f32 v65, v20, s0
	global_store_short v[106:107], v65, off offset:128
	v_cvt_pk_bf16_f32 v65, v21, s0
	global_store_short v[108:109], v65, off offset:128
	v_cvt_pk_bf16_f32 v65, v22, s0
	global_store_short v[110:111], v65, off offset:128
	v_cvt_pk_bf16_f32 v65, v23, s0
	global_store_short v[112:113], v65, off offset:128
	v_cvt_pk_bf16_f32 v65, v24, s0
	global_store_short v[114:115], v65, off offset:128
	v_cvt_pk_bf16_f32 v65, v25, s0
	global_store_short v[116:117], v65, off offset:128
	v_cvt_pk_bf16_f32 v65, v26, s0
	global_store_short v[118:119], v65, off offset:128
	v_cvt_pk_bf16_f32 v65, v27, s0
	global_store_short v[120:121], v65, off offset:128
	v_cvt_pk_bf16_f32 v65, v28, s0
	global_store_short v[122:123], v65, off offset:128
	v_cvt_pk_bf16_f32 v65, v29, s0
	global_store_short v[124:125], v65, off offset:128
	v_cvt_pk_bf16_f32 v65, v30, s0
	global_store_short v[126:127], v65, off offset:128
	v_cvt_pk_bf16_f32 v65, v31, s0
	global_store_short v[96:97], v65, off offset:128
	v_cvt_pk_bf16_f32 v65, v0, s0
	global_store_short v[98:99], v65, off offset:192
	v_cvt_pk_bf16_f32 v65, v1, s0
	global_store_short v[100:101], v65, off offset:192
	v_cvt_pk_bf16_f32 v65, v2, s0
	global_store_short v[102:103], v65, off offset:192
	v_cvt_pk_bf16_f32 v65, v3, s0
; DI bf16 f2bf(float a) { return (bf16)(pack2(a, 0.f) & 0xffffu); }
; DI int crow(int i, int g) { return (i & 3) + 8 * (i >> 2) + 4 * g; }
;     ...
;           for (int i = 0; i < 16; ++i) hb[(size_t)(m0 + 32 * w + crow(i, g)) * 640 + n0 + 32 * j + r] = f2bf(acc[j][i]);
;         float* rss = (float*)(ws + OFF_RSS);
; #pragma unroll
;         for (int i = 0; i < 16; ++i) {
;           float ss = acc[0][i] * acc[0][i] + acc[1][i] * acc[1][i] + acc[2][i] * acc[2][i] + acc[3][i] * acc[3][i];
;           ss += __shfl_xor(ss, 16); ss += __shfl_xor(ss, 8); ss += __shfl_xor(ss, 4); ss += __shfl_xor(ss, 2); ss += __shfl_xor(ss, 1);
;           if (r == 0) rss[(size_t)(m0 + 32 * w + crow(i, g)) * 8 + nt] = ss;
;         }
	global_store_short v[104:105], v65, off offset:192
	v_cvt_pk_bf16_f32 v65, v4, s0
	global_store_short v[106:107], v65, off offset:192
	v_cvt_pk_bf16_f32 v65, v5, s0
	global_store_short v[108:109], v65, off offset:192
	v_cvt_pk_bf16_f32 v65, v6, s0
	global_store_short v[110:111], v65, off offset:192
	v_cvt_pk_bf16_f32 v65, v7, s0
	global_store_short v[112:113], v65, off offset:192
	v_cvt_pk_bf16_f32 v65, v8, s0
	global_store_short v[114:115], v65, off offset:192
	v_cvt_pk_bf16_f32 v65, v9, s0
	global_store_short v[116:117], v65, off offset:192
	v_cvt_pk_bf16_f32 v65, v10, s0
	global_store_short v[118:119], v65, off offset:192
	v_cvt_pk_bf16_f32 v65, v11, s0
	global_store_short v[120:121], v65, off offset:192
	v_cvt_pk_bf16_f32 v65, v12, s0
	global_store_short v[122:123], v65, off offset:192
	v_cvt_pk_bf16_f32 v65, v13, s0
	global_store_short v[124:125], v65, off offset:192
	v_cvt_pk_bf16_f32 v65, v14, s0
	global_store_short v[126:127], v65, off offset:192
	v_cvt_pk_bf16_f32 v65, v15, s0
	global_store_short v[96:97], v65, off offset:192
	v_mul_f32_e32 v32, v32, v32
	v_fmac_f32_e32 v32, v48, v48
	v_fmac_f32_e32 v32, v16, v16
	v_fmac_f32_e32 v32, v0, v0
	s_nop 1
	v_add_f32_dpp v32, v32, v32 quad_perm:[1,0,3,2] row_mask:0xf bank_mask:0xf
	s_nop 1
	v_add_f32_dpp v32, v32, v32 quad_perm:[2,3,0,1] row_mask:0xf bank_mask:0xf
	s_nop 1
	v_add_f32_dpp v32, v32, v32 row_half_mirror row_mask:0xf bank_mask:0xf
	s_nop 1
	v_add_f32_dpp v32, v32, v32 row_mirror row_mask:0xf bank_mask:0xf
	v_mov_b32_e32 v69, v32
	s_nop 1
	v_permlane16_swap_b32_e32 v32, v69
	v_add_f32_e32 v32, v32, v69
	v_mov_b32_e32 v67, v32
	s_ashr_i32 s15, s14, 31
	s_lshl_b64 s[0:1], s[14:15], 2
	s_add_u32 s14, s46, s0
	s_addc_u32 s15, s47, s1
	s_and_saveexec_b64 s[16:17], s[6:7]
	s_cbranch_execz .LBB0_238
	v_ashrrev_i32_e32 v95, 31, v94
	v_lshlrev_b64 v[94:95], 5, v[94:95]
	v_lshl_add_u64 v[94:95], s[14:15], 0, v[94:95]
	s_waitcnt lgkmcnt(0)
	global_store_dword v[94:95], v67, off
.LBB0_238:
	s_or_b64 exec, exec, s[16:17]
	v_mul_f32_e32 v33, v33, v33
	v_fmac_f32_e32 v33, v49, v49
	v_fmac_f32_e32 v33, v17, v17
	v_fmac_f32_e32 v33, v1, v1
	v_mov_b32_e32 v1, v33
	s_nop 1
	v_add_f32_dpp v1, v1, v1 quad_perm:[1,0,3,2] row_mask:0xf bank_mask:0xf
	s_nop 1
	v_add_f32_dpp v1, v1, v1 quad_perm:[2,3,0,1] row_mask:0xf bank_mask:0xf
	s_nop 1
	v_add_f32_dpp v1, v1, v1 row_half_mirror row_mask:0xf bank_mask:0xf
	s_nop 1
	v_add_f32_dpp v1, v1, v1 row_mirror row_mask:0xf bank_mask:0xf
	v_mov_b32_e32 v17, v1
	s_nop 1
	v_permlane16_swap_b32_e32 v1, v17
	v_add_f32_e32 v1, v1, v17
	s_and_saveexec_b64 s[16:17], s[6:7]
	s_cbranch_execz .LBB0_240
	v_ashrrev_i32_e32 v93, 31, v92
	v_lshlrev_b64 v[92:93], 5, v[92:93]
	v_lshl_add_u64 v[92:93], s[14:15], 0, v[92:93]
	s_waitcnt lgkmcnt(0)
	global_store_dword v[92:93], v1, off
.LBB0_240:
	s_or_b64 exec, exec, s[16:17]
	v_mul_f32_e32 v1, v34, v34
	v_fmac_f32_e32 v1, v50, v50
	v_fmac_f32_e32 v1, v18, v18
	v_fmac_f32_e32 v1, v2, v2
	s_nop 1
	v_add_f32_dpp v1, v1, v1 quad_perm:[1,0,3,2] row_mask:0xf bank_mask:0xf
	s_nop 1
	v_add_f32_dpp v1, v1, v1 quad_perm:[2,3,0,1] row_mask:0xf bank_mask:0xf
	s_nop 1
	v_add_f32_dpp v1, v1, v1 row_half_mirror row_mask:0xf bank_mask:0xf
	s_nop 1
	v_add_f32_dpp v1, v1, v1 row_mirror row_mask:0xf bank_mask:0xf
	v_mov_b32_e32 v2, v1
	s_nop 1
	v_permlane16_swap_b32_e32 v1, v2
	v_add_f32_e32 v1, v1, v2
	s_and_saveexec_b64 s[16:17], s[6:7]
	s_cbranch_execz .LBB0_242
	v_ashrrev_i32_e32 v91, 31, v90
	v_lshlrev_b64 v[90:91], 5, v[90:91]
	v_lshl_add_u64 v[90:91], s[14:15], 0, v[90:91]
	s_waitcnt lgkmcnt(0)
	global_store_dword v[90:91], v1, off
.LBB0_242:
	s_or_b64 exec, exec, s[16:17]
	v_mul_f32_e32 v1, v35, v35
	v_fmac_f32_e32 v1, v51, v51
	v_fmac_f32_e32 v1, v19, v19
	v_fmac_f32_e32 v1, v3, v3
	s_waitcnt lgkmcnt(0)
	s_nop 1
	v_add_f32_dpp v1, v1, v1 quad_perm:[1,0,3,2] row_mask:0xf bank_mask:0xf
	s_nop 1
	v_add_f32_dpp v1, v1, v1 quad_perm:[2,3,0,1] row_mask:0xf bank_mask:0xf
	s_nop 1
	v_add_f32_dpp v1, v1, v1 row_half_mirror row_mask:0xf bank_mask:0xf
	s_nop 1
	v_add_f32_dpp v1, v1, v1 row_mirror row_mask:0xf bank_mask:0xf
	v_mov_b32_e32 v2, v1
	s_nop 1
	v_permlane16_swap_b32_e32 v1, v2
	v_add_f32_e32 v1, v1, v2
	s_and_saveexec_b64 s[16:17], s[6:7]
	s_cbranch_execz .LBB0_244
	v_ashrrev_i32_e32 v89, 31, v88
	v_lshlrev_b64 v[18:19], 5, v[88:89]
	v_lshl_add_u64 v[18:19], s[14:15], 0, v[18:19]
	s_waitcnt lgkmcnt(0)
	global_store_dword v[18:19], v1, off
.LBB0_244:
	s_or_b64 exec, exec, s[16:17]
	v_mul_f32_e32 v1, v36, v36
	v_fmac_f32_e32 v1, v52, v52
	v_fmac_f32_e32 v1, v20, v20
	v_fmac_f32_e32 v1, v4, v4
	s_waitcnt lgkmcnt(0)
	s_nop 1
	v_add_f32_dpp v1, v1, v1 quad_perm:[1,0,3,2] row_mask:0xf bank_mask:0xf
	s_nop 1
	v_add_f32_dpp v1, v1, v1 quad_perm:[2,3,0,1] row_mask:0xf bank_mask:0xf
	s_nop 1
	v_add_f32_dpp v1, v1, v1 row_half_mirror row_mask:0xf bank_mask:0xf
	s_nop 1
	v_add_f32_dpp v1, v1, v1 row_mirror row_mask:0xf bank_mask:0xf
	v_mov_b32_e32 v2, v1
	s_nop 1
	v_permlane16_swap_b32_e32 v1, v2
	v_add_f32_e32 v1, v1, v2
	s_and_saveexec_b64 s[16:17], s[6:7]
	s_cbranch_execz .LBB0_246
	v_ashrrev_i32_e32 v87, 31, v86
	v_lshlrev_b64 v[18:19], 5, v[86:87]
	v_lshl_add_u64 v[18:19], s[14:15], 0, v[18:19]
	s_waitcnt lgkmcnt(0)
	global_store_dword v[18:19], v1, off
; DI int crow(int i, int g) { return (i & 3) + 8 * (i >> 2) + 4 * g; }
;     ...
;         float* rss = (float*)(ws + OFF_RSS);
; #pragma unroll
;         for (int i = 0; i < 16; ++i) {
;           float ss = acc[0][i] * acc[0][i] + acc[1][i] * acc[1][i] + acc[2][i] * acc[2][i] + acc[3][i] * acc[3][i];
;           ss += __shfl_xor(ss, 16); ss += __shfl_xor(ss, 8); ss += __shfl_xor(ss, 4); ss += __shfl_xor(ss, 2); ss += __shfl_xor(ss, 1);
;           if (r == 0) rss[(size_t)(m0 + 32 * w + crow(i, g)) * 8 + nt] = ss;
;         }
.LBB0_246:
	s_or_b64 exec, exec, s[16:17]
	v_mul_f32_e32 v1, v37, v37
	v_fmac_f32_e32 v1, v53, v53
	v_fmac_f32_e32 v1, v21, v21
	v_fmac_f32_e32 v1, v5, v5
	s_waitcnt lgkmcnt(0)
	s_nop 1
	v_add_f32_dpp v1, v1, v1 quad_perm:[1,0,3,2] row_mask:0xf bank_mask:0xf
	s_nop 1
	v_add_f32_dpp v1, v1, v1 quad_perm:[2,3,0,1] row_mask:0xf bank_mask:0xf
	s_nop 1
	v_add_f32_dpp v1, v1, v1 row_half_mirror row_mask:0xf bank_mask:0xf
	s_nop 1
	v_add_f32_dpp v1, v1, v1 row_mirror row_mask:0xf bank_mask:0xf
	v_mov_b32_e32 v2, v1
	s_nop 1
	v_permlane16_swap_b32_e32 v1, v2
	v_add_f32_e32 v1, v1, v2
	s_and_saveexec_b64 s[16:17], s[6:7]
	s_cbranch_execz .LBB0_248
	v_ashrrev_i32_e32 v85, 31, v84
	v_lshlrev_b64 v[4:5], 5, v[84:85]
	v_lshl_add_u64 v[4:5], s[14:15], 0, v[4:5]
	s_waitcnt lgkmcnt(0)
	global_store_dword v[4:5], v1, off
.LBB0_248:
	s_or_b64 exec, exec, s[16:17]
	v_mul_f32_e32 v1, v38, v38
	v_fmac_f32_e32 v1, v54, v54
	v_fmac_f32_e32 v1, v22, v22
	v_fmac_f32_e32 v1, v6, v6
	s_waitcnt lgkmcnt(0)
	s_nop 1
	v_add_f32_dpp v1, v1, v1 quad_perm:[1,0,3,2] row_mask:0xf bank_mask:0xf
	s_nop 1
	v_add_f32_dpp v1, v1, v1 quad_perm:[2,3,0,1] row_mask:0xf bank_mask:0xf
	s_nop 1
	v_add_f32_dpp v1, v1, v1 row_half_mirror row_mask:0xf bank_mask:0xf
	s_nop 1
	v_add_f32_dpp v1, v1, v1 row_mirror row_mask:0xf bank_mask:0xf
	v_mov_b32_e32 v2, v1
	s_nop 1
	v_permlane16_swap_b32_e32 v1, v2
	v_add_f32_e32 v1, v1, v2
	s_and_saveexec_b64 s[16:17], s[6:7]
	s_cbranch_execz .LBB0_250
	v_ashrrev_i32_e32 v83, 31, v82
	v_lshlrev_b64 v[4:5], 5, v[82:83]
	v_lshl_add_u64 v[4:5], s[14:15], 0, v[4:5]
	s_waitcnt lgkmcnt(0)
	global_store_dword v[4:5], v1, off
.LBB0_250:
	s_or_b64 exec, exec, s[16:17]
	v_mul_f32_e32 v1, v39, v39
	v_fmac_f32_e32 v1, v55, v55
	v_fmac_f32_e32 v1, v23, v23
	v_fmac_f32_e32 v1, v7, v7
	s_waitcnt lgkmcnt(0)
	s_nop 1
	v_add_f32_dpp v1, v1, v1 quad_perm:[1,0,3,2] row_mask:0xf bank_mask:0xf
	s_nop 1
	v_add_f32_dpp v1, v1, v1 quad_perm:[2,3,0,1] row_mask:0xf bank_mask:0xf
	s_nop 1
	v_add_f32_dpp v1, v1, v1 row_half_mirror row_mask:0xf bank_mask:0xf
	s_nop 1
	v_add_f32_dpp v1, v1, v1 row_mirror row_mask:0xf bank_mask:0xf
	v_mov_b32_e32 v2, v1
	s_nop 1
	v_permlane16_swap_b32_e32 v1, v2
	v_add_f32_e32 v1, v1, v2
	s_and_saveexec_b64 s[16:17], s[6:7]
	s_cbranch_execz .LBB0_252
	v_ashrrev_i32_e32 v81, 31, v80
	v_lshlrev_b64 v[4:5], 5, v[80:81]
	v_lshl_add_u64 v[4:5], s[14:15], 0, v[4:5]
	s_waitcnt lgkmcnt(0)
	global_store_dword v[4:5], v1, off
.LBB0_252:
	s_or_b64 exec, exec, s[16:17]
	v_mul_f32_e32 v1, v40, v40
	v_fmac_f32_e32 v1, v56, v56
	v_fmac_f32_e32 v1, v24, v24
	v_fmac_f32_e32 v1, v8, v8
	s_waitcnt lgkmcnt(0)
	s_nop 1
	v_add_f32_dpp v1, v1, v1 quad_perm:[1,0,3,2] row_mask:0xf bank_mask:0xf
	s_nop 1
	v_add_f32_dpp v1, v1, v1 quad_perm:[2,3,0,1] row_mask:0xf bank_mask:0xf
	s_nop 1
	v_add_f32_dpp v1, v1, v1 row_half_mirror row_mask:0xf bank_mask:0xf
	s_nop 1
	v_add_f32_dpp v1, v1, v1 row_mirror row_mask:0xf bank_mask:0xf
	v_mov_b32_e32 v2, v1
	s_nop 1
	v_permlane16_swap_b32_e32 v1, v2
	v_add_f32_e32 v1, v1, v2
	s_and_saveexec_b64 s[16:17], s[6:7]
	s_cbranch_execz .LBB0_254
	v_ashrrev_i32_e32 v79, 31, v78
	v_lshlrev_b64 v[4:5], 5, v[78:79]
	v_lshl_add_u64 v[4:5], s[14:15], 0, v[4:5]
	s_waitcnt lgkmcnt(0)
	global_store_dword v[4:5], v1, off
.LBB0_254:
	s_or_b64 exec, exec, s[16:17]
	v_mul_f32_e32 v1, v41, v41
	v_fmac_f32_e32 v1, v57, v57
	v_fmac_f32_e32 v1, v25, v25
	v_fmac_f32_e32 v1, v9, v9
	s_waitcnt lgkmcnt(0)
	s_nop 1
	v_add_f32_dpp v1, v1, v1 quad_perm:[1,0,3,2] row_mask:0xf bank_mask:0xf
	s_nop 1
	v_add_f32_dpp v1, v1, v1 quad_perm:[2,3,0,1] row_mask:0xf bank_mask:0xf
	s_nop 1
	v_add_f32_dpp v1, v1, v1 row_half_mirror row_mask:0xf bank_mask:0xf
	s_nop 1
	v_add_f32_dpp v1, v1, v1 row_mirror row_mask:0xf bank_mask:0xf
	v_mov_b32_e32 v2, v1
	s_nop 1
	v_permlane16_swap_b32_e32 v1, v2
	v_add_f32_e32 v1, v1, v2
	s_and_saveexec_b64 s[16:17], s[6:7]
	s_cbranch_execz .LBB0_256
	v_ashrrev_i32_e32 v77, 31, v76
	v_lshlrev_b64 v[4:5], 5, v[76:77]
	v_lshl_add_u64 v[4:5], s[14:15], 0, v[4:5]
	s_waitcnt lgkmcnt(0)
	global_store_dword v[4:5], v1, off
.LBB0_256:
	s_or_b64 exec, exec, s[16:17]
	v_mul_f32_e32 v1, v42, v42
	v_fmac_f32_e32 v1, v58, v58
	v_fmac_f32_e32 v1, v26, v26
	v_fmac_f32_e32 v1, v10, v10
	s_waitcnt lgkmcnt(0)
	s_nop 1
	v_add_f32_dpp v1, v1, v1 quad_perm:[1,0,3,2] row_mask:0xf bank_mask:0xf
	s_nop 1
	v_add_f32_dpp v1, v1, v1 quad_perm:[2,3,0,1] row_mask:0xf bank_mask:0xf
	s_nop 1
	v_add_f32_dpp v1, v1, v1 row_half_mirror row_mask:0xf bank_mask:0xf
	s_nop 1
	v_add_f32_dpp v1, v1, v1 row_mirror row_mask:0xf bank_mask:0xf
	v_mov_b32_e32 v2, v1
	s_nop 1
	v_permlane16_swap_b32_e32 v1, v2
	v_add_f32_e32 v1, v1, v2
	s_and_saveexec_b64 s[16:17], s[6:7]
	s_cbranch_execz .LBB0_258
	v_ashrrev_i32_e32 v75, 31, v74
	v_lshlrev_b64 v[4:5], 5, v[74:75]
	v_lshl_add_u64 v[4:5], s[14:15], 0, v[4:5]
	s_waitcnt lgkmcnt(0)
	global_store_dword v[4:5], v1, off
; DI int crow(int i, int g) { return (i & 3) + 8 * (i >> 2) + 4 * g; }
;     ...
;         float* rss = (float*)(ws + OFF_RSS);
; #pragma unroll
;         for (int i = 0; i < 16; ++i) {
;           float ss = acc[0][i] * acc[0][i] + acc[1][i] * acc[1][i] + acc[2][i] * acc[2][i] + acc[3][i] * acc[3][i];
;           ss += __shfl_xor(ss, 16); ss += __shfl_xor(ss, 8); ss += __shfl_xor(ss, 4); ss += __shfl_xor(ss, 2); ss += __shfl_xor(ss, 1);
;           if (r == 0) rss[(size_t)(m0 + 32 * w + crow(i, g)) * 8 + nt] = ss;
;         }
.LBB0_258:
	s_or_b64 exec, exec, s[16:17]
	v_mul_f32_e32 v1, v43, v43
	v_fmac_f32_e32 v1, v59, v59
	v_fmac_f32_e32 v1, v27, v27
	v_fmac_f32_e32 v1, v11, v11
	s_waitcnt lgkmcnt(0)
	s_nop 1
	v_add_f32_dpp v1, v1, v1 quad_perm:[1,0,3,2] row_mask:0xf bank_mask:0xf
	s_nop 1
	v_add_f32_dpp v1, v1, v1 quad_perm:[2,3,0,1] row_mask:0xf bank_mask:0xf
	s_nop 1
	v_add_f32_dpp v1, v1, v1 row_half_mirror row_mask:0xf bank_mask:0xf
	s_nop 1
	v_add_f32_dpp v1, v1, v1 row_mirror row_mask:0xf bank_mask:0xf
	v_mov_b32_e32 v2, v1
	s_nop 1
	v_permlane16_swap_b32_e32 v1, v2
	v_add_f32_e32 v1, v1, v2
	s_and_saveexec_b64 s[16:17], s[6:7]
	s_cbranch_execz .LBB0_260
	v_ashrrev_i32_e32 v73, 31, v72
	v_lshlrev_b64 v[4:5], 5, v[72:73]
	v_lshl_add_u64 v[4:5], s[14:15], 0, v[4:5]
	s_waitcnt lgkmcnt(0)
	global_store_dword v[4:5], v1, off
.LBB0_260:
	s_or_b64 exec, exec, s[16:17]
	v_mul_f32_e32 v1, v44, v44
	v_fmac_f32_e32 v1, v60, v60
	v_fmac_f32_e32 v1, v28, v28
	v_fmac_f32_e32 v1, v12, v12
	s_waitcnt lgkmcnt(0)
	s_nop 1
	v_add_f32_dpp v1, v1, v1 quad_perm:[1,0,3,2] row_mask:0xf bank_mask:0xf
	s_nop 1
	v_add_f32_dpp v1, v1, v1 quad_perm:[2,3,0,1] row_mask:0xf bank_mask:0xf
	s_nop 1
	v_add_f32_dpp v1, v1, v1 row_half_mirror row_mask:0xf bank_mask:0xf
	s_nop 1
	v_add_f32_dpp v1, v1, v1 row_mirror row_mask:0xf bank_mask:0xf
	v_mov_b32_e32 v2, v1
	s_nop 1
	v_permlane16_swap_b32_e32 v1, v2
	v_add_f32_e32 v1, v1, v2
	s_and_saveexec_b64 s[16:17], s[6:7]
	s_cbranch_execz .LBB0_262
	v_ashrrev_i32_e32 v71, 31, v70
	v_lshlrev_b64 v[4:5], 5, v[70:71]
	v_lshl_add_u64 v[4:5], s[14:15], 0, v[4:5]
	s_waitcnt lgkmcnt(0)
	global_store_dword v[4:5], v1, off
.LBB0_262:
	s_or_b64 exec, exec, s[16:17]
	v_mul_f32_e32 v1, v45, v45
	v_fmac_f32_e32 v1, v61, v61
	v_fmac_f32_e32 v1, v29, v29
	v_fmac_f32_e32 v1, v13, v13
	s_waitcnt lgkmcnt(0)
	s_nop 1
	v_add_f32_dpp v1, v1, v1 quad_perm:[1,0,3,2] row_mask:0xf bank_mask:0xf
	s_nop 1
	v_add_f32_dpp v1, v1, v1 quad_perm:[2,3,0,1] row_mask:0xf bank_mask:0xf
	s_nop 1
	v_add_f32_dpp v1, v1, v1 row_half_mirror row_mask:0xf bank_mask:0xf
	s_nop 1
	v_add_f32_dpp v1, v1, v1 row_mirror row_mask:0xf bank_mask:0xf
	v_mov_b32_e32 v2, v1
	s_nop 1
	v_permlane16_swap_b32_e32 v1, v2
	v_add_f32_e32 v1, v1, v2
	s_and_saveexec_b64 s[16:17], s[6:7]
	s_cbranch_execz .LBB0_264
	v_ashrrev_i32_e32 v69, 31, v68
	v_lshlrev_b64 v[4:5], 5, v[68:69]
	v_lshl_add_u64 v[4:5], s[14:15], 0, v[4:5]
	s_waitcnt lgkmcnt(0)
	global_store_dword v[4:5], v1, off
.LBB0_264:
	s_or_b64 exec, exec, s[16:17]
	v_mul_f32_e32 v1, v46, v46
	v_fmac_f32_e32 v1, v62, v62
	v_fmac_f32_e32 v1, v30, v30
	v_fmac_f32_e32 v1, v14, v14
	s_waitcnt lgkmcnt(0)
	s_nop 1
	v_add_f32_dpp v1, v1, v1 quad_perm:[1,0,3,2] row_mask:0xf bank_mask:0xf
	s_nop 1
	v_add_f32_dpp v1, v1, v1 quad_perm:[2,3,0,1] row_mask:0xf bank_mask:0xf
	s_nop 1
	v_add_f32_dpp v1, v1, v1 row_half_mirror row_mask:0xf bank_mask:0xf
	s_nop 1
	v_add_f32_dpp v1, v1, v1 row_mirror row_mask:0xf bank_mask:0xf
	v_mov_b32_e32 v2, v1
	s_nop 1
	v_permlane16_swap_b32_e32 v1, v2
	v_add_f32_e32 v1, v1, v2
	s_and_saveexec_b64 s[16:17], s[6:7]
	s_cbranch_execz .LBB0_266
	v_ashrrev_i32_e32 v67, 31, v66
	v_lshlrev_b64 v[4:5], 5, v[66:67]
	v_lshl_add_u64 v[4:5], s[14:15], 0, v[4:5]
	s_waitcnt lgkmcnt(0)
	global_store_dword v[4:5], v1, off
.LBB0_266:
	s_or_b64 exec, exec, s[16:17]
	v_mul_f32_e32 v1, v47, v47
	v_fmac_f32_e32 v1, v63, v63
	v_fmac_f32_e32 v1, v31, v31
	v_fmac_f32_e32 v1, v15, v15
	s_waitcnt lgkmcnt(0)
	v_mov_b32_e32 v0, v1
	s_nop 1
	v_add_f32_dpp v0, v0, v0 quad_perm:[1,0,3,2] row_mask:0xf bank_mask:0xf
	s_nop 1
	v_add_f32_dpp v0, v0, v0 quad_perm:[2,3,0,1] row_mask:0xf bank_mask:0xf
	s_nop 1
	v_add_f32_dpp v0, v0, v0 row_half_mirror row_mask:0xf bank_mask:0xf
	s_nop 1
	v_add_f32_dpp v0, v0, v0 row_mirror row_mask:0xf bank_mask:0xf
	v_mov_b32_e32 v1, v0
	s_nop 1
	v_permlane16_swap_b32_e32 v0, v1
	v_add_f32_e32 v0, v0, v1
	s_and_saveexec_b64 s[16:17], s[6:7]
	s_cbranch_execz .LBB0_225
	v_ashrrev_i32_e32 v65, 31, v64
	v_lshlrev_b64 v[2:3], 5, v[64:65]
	v_lshl_add_u64 v[2:3], s[14:15], 0, v[2:3]
	s_waitcnt lgkmcnt(0)
	global_store_dword v[2:3], v0, off
	s_branch .LBB0_225
